# recurrence consumer loop: six VB row reads issued earlier (next to the first two) instead of right before their consumers
# baseline (speedup 1.0000x reference)
; #define LAS __attribute__((address_space(3)))
; __device__ __forceinline__ void delta_rec_task(const Params& P, LAS unsigned char* lds, int b, int h, int tid) {
;     ...
;             for (int s = 0; s < 8; ++s) { const int kb = s >> 1, o = 8 * (s & 1); SB[s] = pack8(S[kb][o], S[kb][o + 1], S[kb][o + 2], S[kb][o + 3], S[kb][o + 4], S[kb][o + 5], S[kb][o + 6], S[kb][o + 7]); }
;             f32x16 X1, P1;
; #pragma unroll
;             for (int r = 0; r < 16; ++r) { X1[r] = 0.f; P1[r] = 0.f; }
;             const LAS bf16* KB = (const LAS bf16*)(buf + DR_KB) + n * 136 + 8 * hh; const LAS bf16* QD = (const LAS bf16*)(buf + DR_QD) + n * 136 + 8 * hh;
; #pragma unroll
;             for (int s = 0; s < 8; ++s) { X1 = __builtin_amdgcn_mfma_f32_32x32x16_bf16(*(const LAS bf16x8*)(KB + 16 * s), SB[s], X1, 0, 0, 0);
;                 P1 = __builtin_amdgcn_mfma_f32_32x32x16_bf16(*(const LAS bf16x8*)(QD + 16 * s), SB[s], P1, 0, 0, 0); }
;             const LAS float* VB = (const LAS float*)(buf + DR_VB) + 32 * vb + n;
;             float Y[16];
; #pragma unroll
;             for (int r = 0; r < 16; ++r) Y[r] = VB[((r & 3) + 8 * (r >> 2) + 4 * hh) * 132] - X1[r];
.LBB0_1833:
	s_and_b32 s4, s3, 1
	s_mul_i32 s5, s4, 0xc210
	s_add_i32 s5, s5, 0
	v_add3_u32 v136, s5, v117, v118
	ds_read_b128 v[64:67], v136
	ds_read_b128 v[96:99], v136 offset:32
	v_cvt_pk_bf16_f32 v80, v48, v49
	v_cvt_pk_bf16_f32 v81, v50, v51
	v_cvt_pk_bf16_f32 v82, v52, v53
	v_cvt_pk_bf16_f32 v83, v54, v55
	ds_read_b128 v[84:87], v136 offset:8704
	ds_read_b128 v[100:103], v136 offset:8736
	s_waitcnt lgkmcnt(3)
	v_mfma_f32_32x32x16_bf16 v[64:79], v[64:67], v[80:83], 0
	v_cvt_pk_bf16_f32 v104, v56, v57
	v_cvt_pk_bf16_f32 v105, v58, v59
	v_cvt_pk_bf16_f32 v106, v60, v61
	v_cvt_pk_bf16_f32 v107, v62, v63
	v_cvt_pk_bf16_f32 v108, v32, v33
	v_cvt_pk_bf16_f32 v109, v34, v35
	v_cvt_pk_bf16_f32 v110, v36, v37
	s_waitcnt vmcnt(0) lgkmcnt(1)
	v_mfma_f32_32x32x16_bf16 v[80:95], v[84:87], v[80:83], 0
	v_cvt_pk_bf16_f32 v111, v38, v39
	v_cvt_pk_bf16_f32 v120, v16, v17
	v_cvt_pk_bf16_f32 v121, v18, v19
	v_cvt_pk_bf16_f32 v122, v20, v21
	v_cvt_pk_bf16_f32 v123, v22, v23
	v_lshl_add_u32 v137, v112, 2, s5
	v_add3_u32 v162, v137, v115, v114
	v_mfma_f32_32x32x16_bf16 v[64:79], v[96:99], v[104:107], v[64:79]
	v_cvt_pk_bf16_f32 v96, v40, v41
	v_cvt_pk_bf16_f32 v97, v42, v43
	v_cvt_pk_bf16_f32 v98, v44, v45
	v_cvt_pk_bf16_f32 v99, v46, v47
	v_mov_b32_e32 v144, s5
	v_add3_u32 v161, s5, v119, v118
	v_add_u32_e32 v163, 0x8000, v162
	s_waitcnt lgkmcnt(0)
	v_mfma_f32_32x32x16_bf16 v[80:95], v[100:103], v[104:107], v[80:95]
	ds_read_b128 v[100:103], v136 offset:64
	ds_read_b128 v[104:107], v136 offset:96
	v_add_u32_e32 v164, 0x8400, v162
	v_add_u32_e32 v165, 0x9000, v162
	v_add_u32_e32 v168, 0x9400, v162
	v_add_u32_e32 v169, 0xa000, v162
	v_add_u32_e32 v170, 0xa400, v162
	v_add_u32_e32 v171, 0xb000, v162
	s_waitcnt lgkmcnt(1)
	v_mfma_f32_32x32x16_bf16 v[64:79], v[100:103], v[108:111], v[64:79]
	ds_read_b128 v[100:103], v136 offset:8768
	ds_read_b128 v[124:127], v136 offset:8800
	v_add_u32_e32 v172, 0xb400, v162
	s_mulk_i32 s4, 0x4200
	s_add_i32 s3, s3, 1
	s_cmp_lg_u32 s3, 64
	s_waitcnt lgkmcnt(1)
	v_mfma_f32_32x32x16_bf16 v[80:95], v[100:103], v[108:111], v[80:95]
	v_cvt_pk_bf16_f32 v100, v24, v25
	v_cvt_pk_bf16_f32 v101, v26, v27
	v_cvt_pk_bf16_f32 v102, v28, v29
	v_cvt_pk_bf16_f32 v103, v30, v31
	v_cvt_pk_bf16_f32 v108, v8, v9
	v_cvt_pk_bf16_f32 v109, v10, v11
	v_cvt_pk_bf16_f32 v110, v12, v13
	v_mfma_f32_32x32x16_bf16 v[64:79], v[104:107], v[96:99], v[64:79]
	v_cvt_pk_bf16_f32 v104, v0, v1
	v_cvt_pk_bf16_f32 v105, v2, v3
	v_cvt_pk_bf16_f32 v106, v4, v5
	v_cvt_pk_bf16_f32 v107, v6, v7
	v_cvt_pk_bf16_f32 v111, v14, v15
	s_waitcnt lgkmcnt(0)
	v_mfma_f32_32x32x16_bf16 v[80:95], v[124:127], v[96:99], v[80:95]
	ds_read_b128 v[96:99], v136 offset:128
	ds_read_b128 v[124:127], v136 offset:160
	s_waitcnt lgkmcnt(1)
	v_mfma_f32_32x32x16_bf16 v[64:79], v[96:99], v[120:123], v[64:79]
	ds_read_b128 v[96:99], v136 offset:8832
	ds_read_b128 v[128:131], v136 offset:8864
	s_waitcnt lgkmcnt(2)
	v_mfma_f32_32x32x16_bf16 v[64:79], v[124:127], v[100:103], v[64:79]
	s_waitcnt lgkmcnt(1)
	v_mfma_f32_32x32x16_bf16 v[80:95], v[96:99], v[120:123], v[80:95]
	ds_read_b128 v[96:99], v136 offset:8896
	ds_read_b128 v[120:123], v136 offset:192
	ds_read_b128 v[132:135], v136 offset:224
	ds_read_b128 v[124:127], v136 offset:8928
	ds_read_b128 v[136:139], v161 offset:27680
	ds_read_b128 v[140:143], v161 offset:30208
	ds_read_b32 v160, v144 offset:49664
	ds_read_b128 v[144:147], v161 offset:17408
	ds_read_b128 v[148:151], v161 offset:19968
	s_waitcnt lgkmcnt(2)
	v_pk_mul_f32 v[62:63], v[62:63], v[160:161] op_sel_hi:[1,0]
	v_pk_mul_f32 v[60:61], v[60:61], v[160:161] op_sel_hi:[1,0]
	v_mfma_f32_32x32x16_bf16 v[64:79], v[120:123], v[104:107], v[64:79]
	v_mul_f32_e64 v58, v58, v160
	v_mul_f32_e64 v59, v59, v160
	v_mul_f32_e64 v56, v56, v160
	v_mul_f32_e64 v57, v57, v160
	v_mul_f32_e64 v54, v54, v160
	v_mul_f32_e64 v55, v55, v160
	v_pk_mul_f32 v[52:53], v[52:53], v[160:161] op_sel_hi:[1,0]
	v_pk_mul_f32 v[50:51], v[50:51], v[160:161] op_sel_hi:[1,0]
	v_pk_mul_f32 v[48:49], v[48:49], v[160:161] op_sel_hi:[1,0]
	v_pk_mul_f32 v[46:47], v[46:47], v[160:161] op_sel_hi:[1,0]
	v_mfma_f32_32x32x16_bf16 v[80:95], v[128:131], v[100:103], v[80:95]
	ds_read_b128 v[128:131], v161 offset:22528
	ds_read_b128 v[152:155], v161 offset:25088
	ds_read_b128 v[100:103], v161 offset:27648
	ds_read_b128 v[156:159], v161 offset:25120
	ds_read2_b32 v[120:121], v163 offset1:132
	ds_read2_b32 v[122:123], v164 offset0:8 offset1:140
	ds_read2_b32 v[192:193], v165 offset0:32 offset1:164
	ds_read2_b32 v[194:195], v168 offset0:40 offset1:172
	ds_read2_b32 v[196:197], v169 offset0:64 offset1:196
	ds_read2_b32 v[162:163], v170 offset0:72 offset1:204
	ds_read2_b32 v[164:165], v171 offset0:96 offset1:228
	ds_read2_b32 v[168:169], v172 offset0:104 offset1:236
	v_pk_mul_f32 v[44:45], v[44:45], v[160:161] op_sel_hi:[1,0]
	v_pk_mul_f32 v[42:43], v[42:43], v[160:161] op_sel_hi:[1,0]
	v_pk_mul_f32 v[40:41], v[40:41], v[160:161] op_sel_hi:[1,0]
	v_pk_mul_f32 v[38:39], v[38:39], v[160:161] op_sel_hi:[1,0]
	v_pk_mul_f32 v[36:37], v[36:37], v[160:161] op_sel_hi:[1,0]
	v_mfma_f32_32x32x16_bf16 v[64:79], v[132:135], v[108:111], v[64:79]
	v_mul_f32_e64 v34, v34, v160
	v_mul_f32_e64 v35, v35, v160
	v_mul_f32_e64 v32, v32, v160
	v_mul_f32_e64 v33, v33, v160
	v_mul_f32_e64 v30, v30, v160
	v_mul_f32_e64 v31, v31, v160
	v_pk_mul_f32 v[28:29], v[28:29], v[160:161] op_sel_hi:[1,0]
	v_pk_mul_f32 v[26:27], v[26:27], v[160:161] op_sel_hi:[1,0]
	v_pk_mul_f32 v[24:25], v[24:25], v[160:161] op_sel_hi:[1,0]
	v_pk_mul_f32 v[22:23], v[22:23], v[160:161] op_sel_hi:[1,0]
	v_mfma_f32_32x32x16_bf16 v[80:95], v[96:99], v[104:107], v[80:95]
	ds_read_b128 v[176:179], v161 offset:17440
	ds_read_b128 v[180:183], v161 offset:20000
	ds_read_b128 v[184:187], v161 offset:22560
	ds_read_b128 v[188:191], v161 offset:30240
	s_waitcnt lgkmcnt(11)
; #define LAS __attribute__((address_space(3)))
; #define DR_BAR() do { asm volatile("s_waitcnt lgkmcnt(0)" ::: "memory"); __builtin_amdgcn_s_barrier(); asm volatile("" ::: "memory"); } while (0)
; __device__ __forceinline__ void delta_rec_task(const Params& P, LAS unsigned char* lds, int b, int h, int tid) {
;     ...
;             for (int r = 0; r < 16; ++r) Y[r] = VB[((r & 3) + 8 * (r >> 2) + 4 * hh) * 132] - X1[r];
;             const bf16x8 YB0 = pack8(Y[0], Y[1], Y[2], Y[3], Y[4], Y[5], Y[6], Y[7]), YB1 = pack8(Y[8], Y[9], Y[10], Y[11], Y[12], Y[13], Y[14], Y[15]);
;             f32x16 VN;
; #pragma unroll
;             for (int r = 0; r < 16; ++r) VN[r] = 0.f;
;             const LAS bf16* TI = (const LAS bf16*)(buf + DR_TI) + n * 40 + 8 * hh; const LAS bf16* AT = (const LAS bf16*)(buf + DR_AT) + n * 40 + 8 * hh;
;             VN = __builtin_amdgcn_mfma_f32_32x32x16_bf16(*(const LAS bf16x8*)TI, YB0, VN, 0, 0, 0);
;             VN = __builtin_amdgcn_mfma_f32_32x32x16_bf16(*(const LAS bf16x8*)(TI + 16), YB1, VN, 0, 0, 0);
;             const bf16x8 VB0 = pack8(VN[0], VN[1], VN[2], VN[3], VN[4], VN[5], VN[6], VN[7]), VB1 = pack8(VN[8], VN[9], VN[10], VN[11], VN[12], VN[13], VN[14], VN[15]);
;             P1 = __builtin_amdgcn_mfma_f32_32x32x16_bf16(*(const LAS bf16x8*)AT, VB0, P1, 0, 0, 0);
;             P1 = __builtin_amdgcn_mfma_f32_32x32x16_bf16(*(const LAS bf16x8*)(AT + 16), VB1, P1, 0, 0, 0);
;             const float egl = *(const LAS float*)(buf + DR_EGL);
;             const LAS bf16* KDT = (const LAS bf16*)(buf + DR_KDT) + n * 40 + 8 * hh;
; #pragma unroll
;             for (int kb = 0; kb < 4; ++kb) {
; #pragma unroll
;                 for (int r = 0; r < 16; ++r) S[kb][r] *= egl;
;                 S[kb] = __builtin_amdgcn_mfma_f32_32x32x16_bf16(*(const LAS bf16x8*)(KDT + kb * 32 * 40), VB0, S[kb], 0, 0, 0);
;                 S[kb] = __builtin_amdgcn_mfma_f32_32x32x16_bf16(*(const LAS bf16x8*)(KDT + kb * 32 * 40 + 16), VB1, S[kb], 0, 0, 0); }
;             LAS float* op = (LAS float*)(lds + DR_OB) + (c & 1) * 32 * 132 + 4 * hh * 132 + 32 * vb + n;
; #pragma unroll
;             for (int r = 0; r < 16; ++r) op[((r & 3) + 8 * (r >> 2)) * 132] = P1[r];
;             DR_BAR();
	v_pk_add_f32 v[64:65], v[120:121], v[64:65] neg_lo:[0,1] neg_hi:[0,1]
	s_waitcnt lgkmcnt(10)
	v_pk_add_f32 v[66:67], v[122:123], v[66:67] neg_lo:[0,1] neg_hi:[0,1]
	s_waitcnt lgkmcnt(9)
	v_pk_add_f32 v[68:69], v[192:193], v[68:69] neg_lo:[0,1] neg_hi:[0,1]
	s_waitcnt lgkmcnt(8)
	v_pk_add_f32 v[70:71], v[194:195], v[70:71] neg_lo:[0,1] neg_hi:[0,1]
	v_cvt_pk_bf16_f32 v64, v64, v65
	v_cvt_pk_bf16_f32 v65, v66, v67
	v_cvt_pk_bf16_f32 v66, v68, v69
	v_cvt_pk_bf16_f32 v67, v70, v71
	v_mfma_f32_32x32x16_bf16 v[80:95], v[124:127], v[108:111], v[80:95]
	s_waitcnt lgkmcnt(7)
	v_add_f32_e64 v72, v196, -v72
	v_add_f32_e64 v73, v197, -v73
	s_waitcnt lgkmcnt(5)
	v_add_f32_e64 v68, v164, -v76
	v_add_f32_e64 v69, v165, -v77
	s_waitcnt lgkmcnt(4)
	v_pk_add_f32 v[70:71], v[168:169], v[78:79] neg_lo:[0,1] neg_hi:[0,1]
	v_pk_mul_f32 v[20:21], v[20:21], v[160:161] op_sel_hi:[1,0]
	v_pk_mul_f32 v[18:19], v[18:19], v[160:161] op_sel_hi:[1,0]
	v_pk_mul_f32 v[16:17], v[16:17], v[160:161] op_sel_hi:[1,0]
	v_pk_mul_f32 v[14:15], v[14:15], v[160:161] op_sel_hi:[1,0]
	v_mfma_f32_32x32x16_bf16 v[96:111], v[100:103], v[64:67], 0
	v_add_f32_e64 v66, v162, -v74
	v_add_f32_e64 v67, v163, -v75
	v_cvt_pk_bf16_f32 v64, v72, v73
	v_cvt_pk_bf16_f32 v65, v66, v67
	v_cvt_pk_bf16_f32 v66, v68, v69
	v_cvt_pk_bf16_f32 v67, v70, v71
	v_pk_mul_f32 v[12:13], v[12:13], v[160:161] op_sel_hi:[1,0]
	v_pk_mul_f32 v[10:11], v[10:11], v[160:161] op_sel_hi:[1,0]
	v_mfma_f32_32x32x16_bf16 v[96:111], v[136:139], v[64:67], v[96:111]
	v_mul_f32_e64 v8, v8, v160
	v_mul_f32_e64 v9, v9, v160
	v_mul_f32_e64 v6, v6, v160
	v_mul_f32_e64 v7, v7, v160
	v_mul_f32_e64 v4, v4, v160
	v_mul_f32_e64 v5, v5, v160
	v_pk_mul_f32 v[2:3], v[2:3], v[160:161] op_sel_hi:[1,0]
	v_pk_mul_f32 v[0:1], v[0:1], v[160:161] op_sel_hi:[1,0]
	v_add_u32_e32 v72, s4, v116
	v_add_u32_e32 v73, 0x400, v72
	s_nop 1
	v_cvt_pk_bf16_f32 v64, v96, v97
	v_cvt_pk_bf16_f32 v65, v98, v99
	v_cvt_pk_bf16_f32 v66, v100, v101
	v_cvt_pk_bf16_f32 v67, v102, v103
	v_cvt_pk_bf16_f32 v68, v104, v105
	v_cvt_pk_bf16_f32 v69, v106, v107
	v_mfma_f32_32x32x16_bf16 v[48:63], v[144:147], v[64:67], v[48:63]
	v_cvt_pk_bf16_f32 v70, v108, v109
	v_cvt_pk_bf16_f32 v71, v110, v111
	v_add_u32_e32 v74, 0x1000, v72
	v_add_u32_e32 v75, 0x1400, v72
	v_add_u32_e32 v76, 0x2000, v72
	v_add_u32_e32 v77, 0x2400, v72
	v_add_u32_e32 v78, 0x3000, v72
	v_mfma_f32_32x32x16_bf16 v[32:47], v[148:151], v[64:67], v[32:47]
	v_add_u32_e32 v79, 0x3400, v72
	v_mfma_f32_32x32x16_bf16 v[16:31], v[128:131], v[64:67], v[16:31]
	v_mfma_f32_32x32x16_bf16 v[0:15], v[152:155], v[64:67], v[0:15]
	v_mfma_f32_32x32x16_bf16 v[80:95], v[140:143], v[64:67], v[80:95]
	s_waitcnt lgkmcnt(0)
	v_mfma_f32_32x32x16_bf16 v[48:63], v[176:179], v[68:71], v[48:63]
	v_mfma_f32_32x32x16_bf16 v[32:47], v[180:183], v[68:71], v[32:47]
	v_mfma_f32_32x32x16_bf16 v[16:31], v[184:187], v[68:71], v[16:31]
	v_mfma_f32_32x32x16_bf16 v[80:95], v[188:191], v[68:71], v[80:95]
	s_nop 11
	ds_write2_b32 v72, v80, v81 offset1:132
	ds_write2_b32 v73, v82, v83 offset0:8 offset1:140
	ds_write2_b32 v74, v84, v85 offset0:32 offset1:164
	ds_write2_b32 v75, v86, v87 offset0:40 offset1:172
	ds_write2_b32 v76, v88, v89 offset0:64 offset1:196
	ds_write2_b32 v77, v90, v91 offset0:72 offset1:204
	ds_write2_b32 v78, v92, v93 offset0:96 offset1:228
	ds_write2_b32 v79, v94, v95 offset0:104 offset1:236
	v_mfma_f32_32x32x16_bf16 v[0:15], v[156:159], v[68:71], v[0:15]
	s_waitcnt lgkmcnt(0)
	s_barrier
	s_cbranch_scc1 .LBB0_1833
	s_andn2_saveexec_b64 s[6:7], s[6:7]
	s_cbranch_execz .LBB0_1818
